# speedup vs baseline: 1.0148x; 1.0148x over previous
; __global__ void __launch_bounds__(NTHREADS) fwd_megakernel(Params p) {
;     ...
;       if (step == 0 || (step == 9 && layer == 0)) {
;         const int cset = (step == 9) ? 2 : (layer == 0 ? 4 : 3);
;         if (gridDim.x == 256) {
;           if (bidx() >= 128) { __syncthreads(); convert_set(ws, cset, bidx() - 128, 128, (float*)lds, wv_); }
;         } else {
;           __syncthreads();
;           convert_set(ws, cset, bidx(), gridDim.x, (float*)lds, wv_);
;         }
.LBB0_1264:
	v_readlane_b32 s2, v254, 27
	s_cmp_eq_u32 s2, 0
	s_cbranch_scc1 .LBB0_1266
	s_cmp_eq_u32 s2, 9
	v_readlane_b32 s4, v254, 23
	s_cselect_b64 s[2:3], -1, 0
	v_readlane_b32 s5, v254, 24
	s_nop 3
	s_and_b64 s[4:5], s[4:5], exec
	s_cselect_b32 s12, 2, 6
	s_branch .LBB0_1267

; __device__ __forceinline__ void convert_set(unsigned char* ws, int set, int gi, int ng, float* lds, int wv_) {
;     ...
;   } else {
;     conv_run(inp(ws, 8) + fw, (u16*)(ws + OFF_W13_11), D_, F_, 1, base, lds, gi, ng, wv_);
;     conv_run(inp(ws, 9) + fw, (u16*)(ws + OFF_W13_11), D_, F_, 2, base, lds, gi, ng, wv_);
;     conv_run(inp(ws, 10) + fw, (u16*)(ws + OFF_W2_11), F_, D_, 0, base, lds, gi, ng, wv_);
.LBB0_1494:
	v_readlane_b32 s8, v254, 27
	s_nop 3
	s_cmp_eq_u32 s8, 9
	s_cbranch_scc0 .Lset3_normal
	s_mov_b64 s[4:5], 0
	s_branch .LBB0_1503

; __device__ __forceinline__ void convert_set(unsigned char* ws, int set, int gi, int ng, float* lds, int wv_) {
;     ...
;     conv_run(inp(ws, 10) + fw, (u16*)(ws + OFF_W2_11), F_, D_, 0, base, lds, gi, ng, wv_);
.LBB0_1503:
	v_readlane_b32 s16, v254, 27
	s_nop 3
	s_cmp_eq_u32 s16, 0
	s_cbranch_scc0 .Lw2_run
	v_readlane_b32 s16, v253, 40
	v_readlane_b32 s17, v253, 41
	s_branch .LBB0_1508
